# ret_out items: K fragments of the 7 conditional key blocks prefetched from LDS alongside block 0 (no per-block LDS round trip)
# baseline (speedup 1.0000x reference)
.LBB0_723:
	s_bfe_u32 s88, s91, 0x30005
	v_cvt_f32_ubyte0_e32 v0, s88
	v_sub_f32_e32 v0, 0xc0a00000, v0
	s_mov_b32 s0, 0xc2fc0000
	v_cmp_gt_f32_e64 s[0:1], s0, v0
	s_ashr_i32 s92, s91, 8
	s_waitcnt vmcnt(0)
	v_cndmask_b32_e64 v1, 0, v27, s[0:1]
	v_add_f32_e32 v0, v0, v1
	v_exp_f32_e32 v0, v0
	s_and_b64 s[0:1], s[0:1], exec
	s_cselect_b32 s0, 0xffffffc0, 0
	s_ashr_i32 s93, s92, 31
	v_ldexp_f32 v0, v0, s0
	s_lshl_b64 s[0:1], s[92:93], 12
	s_and_b32 s89, s33, 0xf80
	s_or_b32 s92, s0, s89
	v_sub_f32_e32 v10, 1.0, v0
	s_lshl_b32 s2, s88, 7
	v_mov_b32_e32 v1, s1
	v_or_b32_e32 v0, s92, v26
	v_lshl_add_u64 v[4:5], v[30:31], 0, s[2:3]
	v_lshlrev_b64 v[8:9], 10, v[0:1]
	v_lshl_add_u64 v[0:1], v[4:5], 0, v[8:9]
	global_load_dwordx4 v[120:123], v[0:1], off nt
	v_lshl_add_u64 v[6:7], v[32:33], 0, s[2:3]
	s_mov_b32 s93, s1
	v_add_u32_e32 v24, s89, v42
	v_lshl_add_u64 v[40:41], s[0:1], 0, v[24:25]
	v_log_f32_e32 v39, v10
	v_lshl_add_u64 v[0:1], v[6:7], 0, v[8:9]
	global_load_dwordx4 v[124:127], v[0:1], off nt
	v_lshl_add_u64 v[0:1], s[92:93], 0, v[28:29]
	v_lshlrev_b64 v[8:9], 10, v[0:1]
	v_lshl_add_u64 v[0:1], v[4:5], 0, v[8:9]
	global_load_dwordx4 v[128:131], v[0:1], off nt
	v_lshl_add_u64 v[0:1], v[6:7], 0, v[8:9]
	global_load_dwordx4 v[132:135], v[0:1], off nt
	global_load_dwordx4 v[136:139], v[34:35], off nt
	v_lshlrev_b64 v[0:1], 10, v[40:41]
	v_lshl_add_u64 v[0:1], s[94:95], 0, v[0:1]
	v_lshl_add_u64 v[0:1], v[0:1], 0, s[2:3]
	v_lshl_add_u64 v[0:1], v[0:1], 0, v[36:37]
	global_load_dwordx4 v[4:7], v[0:1], off nt
	s_nop 0
	global_load_dwordx4 v[0:3], v[0:1], off offset:64 nt
	s_barrier
	s_waitcnt vmcnt(6)
	ds_write_b128 v78, v[120:123]
	s_waitcnt vmcnt(5)
	ds_write_b128 v78, v[124:127] offset:18432
	s_waitcnt vmcnt(4)
	ds_write_b128 v79, v[128:131]
	s_waitcnt vmcnt(3)
	ds_write_b128 v79, v[132:135] offset:18432
	s_waitcnt vmcnt(2)
	ds_write_b128 v80, v[136:139] offset:36864
	s_waitcnt lgkmcnt(0)
	s_barrier
	ds_read_b128 v[8:11], v81
	ds_read_b128 v[12:15], v81 offset:64
	ds_read_b128 v[152:155], v81 offset:2304
	ds_read_b128 v[156:159], v81 offset:2368
	ds_read_b128 v[160:163], v81 offset:4608
	ds_read_b128 v[164:167], v81 offset:4672
	ds_read_b128 v[168:171], v81 offset:6912
	ds_read_b128 v[172:175], v81 offset:6976
	ds_read_b128 v[176:179], v81 offset:9216
	ds_read_b128 v[180:183], v81 offset:9280
	ds_read_b128 v[184:187], v81 offset:11520
	ds_read_b128 v[188:191], v81 offset:11584
	ds_read_b128 v[192:195], v81 offset:13824
	ds_read_b128 v[196:199], v81 offset:13888
	ds_read_b128 v[204:207], v81 offset:16128
	ds_read_b128 v[208:211], v81 offset:16192
	s_waitcnt vmcnt(1) lgkmcnt(15)
	v_mfma_f32_16x16x32_bf16 v[8:11], v[8:11], v[4:7], 0
	s_waitcnt vmcnt(0) lgkmcnt(14)
	v_mfma_f32_16x16x32_bf16 v[8:11], v[12:15], v[0:3], v[8:11]
	s_waitcnt lgkmcnt(0)
	v_lshlrev_b64 v[150:151], 10, v[40:41]
	v_lshl_add_u64 v[150:151], v[150:151], 0, s[96:97]
	v_mov_b32_e32 v148, v38
	v_mov_b32_e32 v149, 0
	v_lshl_add_u64 v[150:151], v[150:151], 0, s[2:3]
	v_lshl_add_u64 v[150:151], v[150:151], 0, v[148:149]
	global_load_dwordx2 v[140:141], v[150:151], off nt
	global_load_dwordx2 v[142:143], v[150:151], off offset:32 nt
	global_load_dwordx2 v[144:145], v[150:151], off offset:64 nt
	global_load_dwordx2 v[146:147], v[150:151], off offset:96 nt
	v_mov_b32_e32 v12, 0
	v_mov_b32_e32 v13, 0
	v_mov_b32_e32 v14, 0
	v_mov_b32_e32 v15, 0
	s_and_saveexec_b64 s[0:1], s[10:11]
	s_cbranch_execz .LBB0_725
	v_mfma_f32_16x16x32_bf16 v[12:15], v[152:155], v[4:7], 0
	v_mfma_f32_16x16x32_bf16 v[12:15], v[156:159], v[0:3], v[12:15]
	v_mul_f32_e32 v16, v39, v47
	v_mul_f32_e32 v17, v39, v48
	v_mul_f32_e32 v18, v39, v49
	v_mul_f32_e32 v19, v39, v50
	v_exp_f32_e32 v16, v16
	v_exp_f32_e32 v17, v17
	v_exp_f32_e32 v18, v18
	v_exp_f32_e32 v19, v19
	v_pk_mul_f32 v[12:13], v[16:17], v[12:13]
	s_nop 0
	v_cndmask_b32_e64 v12, 0, v12, s[30:31]
	v_pk_mul_f32 v[14:15], v[18:19], v[14:15]
	v_cndmask_b32_e64 v13, 0, v13, s[28:29]
	v_cndmask_b32_e64 v14, 0, v14, s[26:27]
	v_cndmask_b32_e64 v15, 0, v15, s[24:25]
.LBB0_725:
	s_or_b64 exec, exec, s[0:1]
	v_mov_b32_e32 v24, 0
	v_mov_b32_e32 v85, 0
	v_mov_b32_e32 v86, 0
	v_mov_b32_e32 v88, 0
	v_mov_b32_e32 v90, 0
	s_and_saveexec_b64 s[0:1], s[12:13]
	s_cbranch_execz .LBB0_727
	v_mfma_f32_16x16x32_bf16 v[16:19], v[160:163], v[4:7], 0
	v_mfma_f32_16x16x32_bf16 v[16:19], v[164:167], v[0:3], v[16:19]
	v_mul_f32_e32 v20, v39, v51
	v_mul_f32_e32 v21, v39, v52
	v_mul_f32_e32 v22, v39, v53
	v_mul_f32_e32 v23, v39, v54
	v_exp_f32_e32 v20, v20
	v_exp_f32_e32 v21, v21
	v_exp_f32_e32 v22, v22
	v_exp_f32_e32 v23, v23
	v_pk_mul_f32 v[16:17], v[20:21], v[16:17]
	s_nop 0
	v_cndmask_b32_e64 v85, 0, v16, s[40:41]
	v_pk_mul_f32 v[18:19], v[22:23], v[18:19]
	v_cndmask_b32_e64 v86, 0, v17, s[38:39]
	v_cndmask_b32_e64 v88, 0, v18, s[36:37]
	v_cndmask_b32_e64 v90, 0, v19, s[34:35]
.LBB0_727:
	s_or_b64 exec, exec, s[0:1]
	v_mov_b32_e32 v98, 0
	v_mov_b32_e32 v99, 0
	v_mov_b32_e32 v101, 0
	s_and_saveexec_b64 s[0:1], s[14:15]
	s_cbranch_execz .LBB0_729
	v_mfma_f32_16x16x32_bf16 v[16:19], v[168:171], v[4:7], 0
	v_mfma_f32_16x16x32_bf16 v[16:19], v[172:175], v[0:3], v[16:19]
	v_mul_f32_e32 v20, v39, v55
	v_mul_f32_e32 v21, v39, v56
	v_mul_f32_e32 v22, v39, v57
	v_mul_f32_e32 v23, v39, v58
	v_exp_f32_e32 v20, v20
	v_exp_f32_e32 v21, v21
	v_exp_f32_e32 v22, v22
	v_exp_f32_e32 v23, v23
	v_pk_mul_f32 v[16:17], v[20:21], v[16:17]
	s_nop 0
	v_cndmask_b32_e64 v24, 0, v16, s[48:49]
	v_pk_mul_f32 v[18:19], v[22:23], v[18:19]
	v_cndmask_b32_e64 v98, 0, v17, s[46:47]
	v_cndmask_b32_e64 v99, 0, v18, s[44:45]
	v_cndmask_b32_e64 v101, 0, v19, s[42:43]
.LBB0_729:
	s_or_b64 exec, exec, s[0:1]
	v_mov_b32_e32 v84, 0
	v_mov_b32_e32 v87, 0
	v_mov_b32_e32 v89, 0
	v_mov_b32_e32 v91, 0
	v_mov_b32_e32 v92, 0
	s_and_saveexec_b64 s[0:1], s[16:17]
	s_cbranch_execz .LBB0_731
	v_mfma_f32_16x16x32_bf16 v[16:19], v[176:179], v[4:7], 0
	v_mfma_f32_16x16x32_bf16 v[16:19], v[180:183], v[0:3], v[16:19]
	v_mul_f32_e32 v20, v39, v59
	v_mul_f32_e32 v21, v39, v60
	v_mul_f32_e32 v22, v39, v61
	v_mul_f32_e32 v23, v39, v62
	v_exp_f32_e32 v20, v20
	v_exp_f32_e32 v21, v21
	v_exp_f32_e32 v22, v22
	v_exp_f32_e32 v23, v23
	v_pk_mul_f32 v[16:17], v[20:21], v[16:17]
	s_nop 0
	v_cndmask_b32_e64 v87, 0, v16, s[56:57]
	v_pk_mul_f32 v[18:19], v[22:23], v[18:19]
	v_cndmask_b32_e64 v89, 0, v17, s[54:55]
	v_cndmask_b32_e64 v91, 0, v18, s[52:53]
	v_cndmask_b32_e64 v92, 0, v19, s[50:51]
.LBB0_731:
	s_or_b64 exec, exec, s[0:1]
	v_mov_b32_e32 v100, 0
	v_mov_b32_e32 v102, 0
	v_mov_b32_e32 v103, 0
	s_and_saveexec_b64 s[0:1], s[18:19]
	s_cbranch_execz .LBB0_733
	v_mfma_f32_16x16x32_bf16 v[16:19], v[184:187], v[4:7], 0
	v_mfma_f32_16x16x32_bf16 v[16:19], v[188:191], v[0:3], v[16:19]
	v_mul_f32_e32 v20, v39, v63
	v_mul_f32_e32 v21, v39, v64
	v_mul_f32_e32 v22, v39, v65
	v_mul_f32_e32 v23, v39, v66
	v_exp_f32_e32 v20, v20
	v_exp_f32_e32 v21, v21
	v_exp_f32_e32 v22, v22
	v_exp_f32_e32 v23, v23
	v_pk_mul_f32 v[16:17], v[20:21], v[16:17]
	s_nop 0
	v_cndmask_b32_e64 v84, 0, v16, s[64:65]
	v_pk_mul_f32 v[18:19], v[22:23], v[18:19]
	v_cndmask_b32_e64 v100, 0, v17, s[62:63]
	v_cndmask_b32_e64 v102, 0, v18, s[60:61]
	v_cndmask_b32_e64 v103, 0, v19, s[58:59]
.LBB0_733:
	s_or_b64 exec, exec, s[0:1]
	v_mov_b32_e32 v93, 0
	v_mov_b32_e32 v94, 0
	v_mov_b32_e32 v95, 0
	v_mov_b32_e32 v96, 0
	v_mov_b32_e32 v97, 0
	s_and_saveexec_b64 s[0:1], s[82:83]
	s_cbranch_execz .LBB0_735
	v_mfma_f32_16x16x32_bf16 v[16:19], v[192:195], v[4:7], 0
	v_mfma_f32_16x16x32_bf16 v[16:19], v[196:199], v[0:3], v[16:19]
	v_mul_f32_e32 v20, v39, v67
	v_mul_f32_e32 v21, v39, v68
	v_mul_f32_e32 v22, v39, v69
	v_mul_f32_e32 v23, v39, v70
	v_exp_f32_e32 v20, v20
	v_exp_f32_e32 v21, v21
	v_exp_f32_e32 v22, v22
	v_exp_f32_e32 v23, v23
	v_pk_mul_f32 v[16:17], v[20:21], v[16:17]
	s_nop 0
	v_cndmask_b32_e64 v94, 0, v16, s[72:73]
	v_pk_mul_f32 v[18:19], v[22:23], v[18:19]
	v_cndmask_b32_e64 v95, 0, v17, s[70:71]
	v_cndmask_b32_e64 v96, 0, v18, s[68:69]
	v_cndmask_b32_e64 v97, 0, v19, s[66:67]
.LBB0_735:
	s_or_b64 exec, exec, s[0:1]
	v_mov_b32_e32 v104, 0
	v_mov_b32_e32 v105, 0
	v_mov_b32_e32 v106, 0
	s_and_saveexec_b64 s[0:1], s[84:85]
	s_cbranch_execz .LBB0_737
	v_mfma_f32_16x16x32_bf16 v[16:19], v[204:207], v[4:7], 0
	v_mfma_f32_16x16x32_bf16 v[16:19], v[208:211], v[0:3], v[16:19]
	v_mul_f32_e32 v20, v39, v71
	v_mul_f32_e32 v21, v39, v72
	v_mul_f32_e32 v22, v39, v73
	v_mul_f32_e32 v23, v39, v74
	v_exp_f32_e32 v20, v20
	v_exp_f32_e32 v21, v21
	v_exp_f32_e32 v22, v22
	v_exp_f32_e32 v23, v23
	v_pk_mul_f32 v[16:17], v[20:21], v[16:17]
	s_nop 0
	v_cndmask_b32_e64 v93, 0, v16, s[80:81]
	v_pk_mul_f32 v[18:19], v[22:23], v[18:19]
	v_cndmask_b32_e64 v104, 0, v17, s[78:79]
	v_cndmask_b32_e64 v105, 0, v18, s[76:77]
	v_cndmask_b32_e64 v106, 0, v19, s[74:75]

.LBB0_748:
	s_bfe_u32 s87, s86, 0x30005
	v_cvt_f32_ubyte0_e32 v0, s87
	v_sub_f32_e32 v0, 0xc0a00000, v0
	s_mov_b32 s0, 0xc2fc0000
	v_cmp_gt_f32_e64 s[0:1], s0, v0
	s_ashr_i32 s88, s86, 8
	s_waitcnt vmcnt(0)
	v_cndmask_b32_e64 v1, 0, v27, s[0:1]
	v_add_f32_e32 v0, v0, v1
	v_exp_f32_e32 v0, v0
	s_and_b64 s[0:1], s[0:1], exec
	s_cselect_b32 s0, 0xffffffc0, 0
	s_ashr_i32 s89, s88, 31
	v_ldexp_f32 v0, v0, s0
	s_lshl_b64 s[0:1], s[88:89], 12
	s_and_b32 s90, s33, 0xf80
	s_or_b32 s88, s0, s90
	v_sub_f32_e32 v10, 1.0, v0
	s_lshl_b32 s2, s87, 7
	v_mov_b32_e32 v1, s1
	v_or_b32_e32 v0, s88, v26
	v_lshl_add_u64 v[4:5], v[30:31], 0, s[2:3]
	v_lshlrev_b64 v[8:9], 10, v[0:1]
	v_lshl_add_u64 v[0:1], v[4:5], 0, v[8:9]
	global_load_dwordx4 v[120:123], v[0:1], off nt
	v_lshl_add_u64 v[6:7], v[32:33], 0, s[2:3]
	s_mov_b32 s89, s1
	v_add_u32_e32 v24, s90, v42
	v_lshl_add_u64 v[40:41], s[0:1], 0, v[24:25]
	v_log_f32_e32 v39, v10
	v_lshl_add_u64 v[0:1], v[6:7], 0, v[8:9]
	global_load_dwordx4 v[124:127], v[0:1], off nt
	v_lshl_add_u64 v[0:1], s[88:89], 0, v[28:29]
	v_lshlrev_b64 v[8:9], 10, v[0:1]
	v_lshl_add_u64 v[0:1], v[4:5], 0, v[8:9]
	global_load_dwordx4 v[128:131], v[0:1], off nt
	v_lshl_add_u64 v[0:1], v[6:7], 0, v[8:9]
	global_load_dwordx4 v[132:135], v[0:1], off nt
	global_load_dwordx4 v[136:139], v[34:35], off nt
	v_lshlrev_b64 v[0:1], 10, v[40:41]
	v_lshl_add_u64 v[0:1], s[94:95], 0, v[0:1]
	v_lshl_add_u64 v[0:1], v[0:1], 0, s[2:3]
	v_lshl_add_u64 v[0:1], v[0:1], 0, v[36:37]
	global_load_dwordx4 v[4:7], v[0:1], off nt
	s_nop 0
	global_load_dwordx4 v[0:3], v[0:1], off offset:64 nt
	s_barrier
	s_waitcnt vmcnt(6)
	ds_write_b128 v78, v[120:123]
	s_waitcnt vmcnt(5)
	ds_write_b128 v78, v[124:127] offset:18432
	s_waitcnt vmcnt(4)
	ds_write_b128 v79, v[128:131]
	s_waitcnt vmcnt(3)
	ds_write_b128 v79, v[132:135] offset:18432
	s_waitcnt vmcnt(2)
	ds_write_b128 v80, v[136:139] offset:36864
	s_waitcnt lgkmcnt(0)
	s_barrier
	ds_read_b128 v[8:11], v81
	ds_read_b128 v[12:15], v81 offset:64
	ds_read_b128 v[152:155], v81 offset:2304
	ds_read_b128 v[156:159], v81 offset:2368
	ds_read_b128 v[160:163], v81 offset:4608
	ds_read_b128 v[164:167], v81 offset:4672
	ds_read_b128 v[168:171], v81 offset:6912
	ds_read_b128 v[172:175], v81 offset:6976
	ds_read_b128 v[176:179], v81 offset:9216
	ds_read_b128 v[180:183], v81 offset:9280
	ds_read_b128 v[184:187], v81 offset:11520
	ds_read_b128 v[188:191], v81 offset:11584
	ds_read_b128 v[192:195], v81 offset:13824
	ds_read_b128 v[196:199], v81 offset:13888
	ds_read_b128 v[204:207], v81 offset:16128
	ds_read_b128 v[208:211], v81 offset:16192
	s_waitcnt vmcnt(1) lgkmcnt(15)
	v_mfma_f32_16x16x32_bf16 v[8:11], v[8:11], v[4:7], 0
	s_waitcnt vmcnt(0) lgkmcnt(14)
	v_mfma_f32_16x16x32_bf16 v[8:11], v[12:15], v[0:3], v[8:11]
	s_waitcnt lgkmcnt(0)
	v_lshlrev_b64 v[150:151], 10, v[40:41]
	v_lshl_add_u64 v[150:151], v[150:151], 0, s[96:97]
	v_mov_b32_e32 v148, v38
	v_mov_b32_e32 v149, 0
	v_lshl_add_u64 v[150:151], v[150:151], 0, s[2:3]
	v_lshl_add_u64 v[150:151], v[150:151], 0, v[148:149]
	global_load_dwordx2 v[140:141], v[150:151], off nt
	global_load_dwordx2 v[142:143], v[150:151], off offset:32 nt
	global_load_dwordx2 v[144:145], v[150:151], off offset:64 nt
	global_load_dwordx2 v[146:147], v[150:151], off offset:96 nt
	v_mov_b32_e32 v12, 0
	v_mov_b32_e32 v13, 0
	v_mov_b32_e32 v14, 0
	v_mov_b32_e32 v15, 0
	s_and_saveexec_b64 s[0:1], s[10:11]
	s_cbranch_execz .LBB0_750
	v_mfma_f32_16x16x32_bf16 v[12:15], v[152:155], v[4:7], 0
	v_mfma_f32_16x16x32_bf16 v[12:15], v[156:159], v[0:3], v[12:15]
	v_mul_f32_e32 v16, v39, v47
	v_mul_f32_e32 v17, v39, v48
	v_mul_f32_e32 v18, v39, v49
	v_mul_f32_e32 v19, v39, v50
	v_exp_f32_e32 v16, v16
	v_exp_f32_e32 v17, v17
	v_exp_f32_e32 v18, v18
	v_exp_f32_e32 v19, v19
	v_pk_mul_f32 v[12:13], v[16:17], v[12:13]
	s_nop 0
	v_cndmask_b32_e64 v12, 0, v12, s[30:31]
	v_pk_mul_f32 v[14:15], v[18:19], v[14:15]
	v_cndmask_b32_e64 v13, 0, v13, s[28:29]
	v_cndmask_b32_e64 v14, 0, v14, s[26:27]
	v_cndmask_b32_e64 v15, 0, v15, s[24:25]

.LBB0_795:
	s_bfe_u32 s88, s87, 0x30005
	v_cvt_f32_ubyte0_e32 v0, s88
	v_sub_f32_e32 v0, 0xc0a00000, v0
	s_mov_b32 s0, 0xc2fc0000
	v_cmp_gt_f32_e64 s[0:1], s0, v0
	s_lshr_b32 s2, s87, 8
	s_nop 0
	v_cndmask_b32_e64 v1, 0, v74, s[0:1]
	v_add_f32_e32 v0, v0, v1
	v_exp_f32_e32 v0, v0
	s_and_b64 s[0:1], s[0:1], exec
	s_cselect_b32 s0, 0xffffffc0, 0
	s_and_b32 s89, s86, 0xf80
	v_ldexp_f32 v0, v0, s0
	s_lshl_b64 s[0:1], s[2:3], 12
	s_or_b32 s90, s0, s89
	v_sub_f32_e32 v10, 1.0, v0
	s_lshl_b32 s2, s88, 7
	v_mov_b32_e32 v1, s1
	v_or_b32_e32 v0, s90, v128
	v_lshl_add_u64 v[4:5], v[28:29], 0, s[2:3]
	v_lshlrev_b64 v[8:9], 10, v[0:1]
	v_lshl_add_u64 v[0:1], v[4:5], 0, v[8:9]
	global_load_dwordx4 v[140:143], v[0:1], off nt
	v_lshl_add_u64 v[6:7], v[30:31], 0, s[2:3]
	s_mov_b32 s91, s1
	v_add_u32_e32 v24, s89, v40
	v_lshl_add_u64 v[38:39], s[0:1], 0, v[24:25]
	v_log_f32_e32 v37, v10
	v_lshl_add_u64 v[0:1], v[6:7], 0, v[8:9]
	global_load_dwordx4 v[144:147], v[0:1], off nt
	v_lshl_add_u64 v[0:1], s[90:91], 0, v[26:27]
	v_lshlrev_b64 v[8:9], 10, v[0:1]
	v_lshl_add_u64 v[0:1], v[4:5], 0, v[8:9]
	global_load_dwordx4 v[148:151], v[0:1], off nt
	v_lshl_add_u64 v[0:1], v[6:7], 0, v[8:9]
	global_load_dwordx4 v[152:155], v[0:1], off nt
	global_load_dwordx4 v[156:159], v[32:33], off nt
	v_lshlrev_b64 v[0:1], 10, v[38:39]
	v_lshl_add_u64 v[0:1], s[94:95], 0, v[0:1]
	v_lshl_add_u64 v[0:1], v[0:1], 0, s[2:3]
	v_lshl_add_u64 v[0:1], v[0:1], 0, v[34:35]
	global_load_dwordx4 v[4:7], v[0:1], off nt
	s_nop 0
	global_load_dwordx4 v[0:3], v[0:1], off offset:64 nt
	s_barrier
	s_waitcnt vmcnt(6)
	ds_write_b128 v75, v[140:143]
	s_waitcnt vmcnt(5)
	ds_write_b128 v75, v[144:147] offset:18432
	s_waitcnt vmcnt(4)
	ds_write_b128 v76, v[148:151]
	s_waitcnt vmcnt(3)
	ds_write_b128 v76, v[152:155] offset:18432
	s_waitcnt vmcnt(2)
	ds_write_b128 v77, v[156:159] offset:36864
	s_waitcnt lgkmcnt(0)
	s_barrier
	ds_read_b128 v[8:11], v78
	ds_read_b128 v[12:15], v78 offset:64
	ds_read_b128 v[172:175], v78 offset:2304
	ds_read_b128 v[176:179], v78 offset:2368
	ds_read_b128 v[180:183], v78 offset:4608
	ds_read_b128 v[184:187], v78 offset:4672
	ds_read_b128 v[188:191], v78 offset:6912
	ds_read_b128 v[192:195], v78 offset:6976
	ds_read_b128 v[204:207], v78 offset:9216
	ds_read_b128 v[208:211], v78 offset:9280
	ds_read_b128 v[212:215], v78 offset:11520
	ds_read_b128 v[216:219], v78 offset:11584
	ds_read_b128 v[220:223], v78 offset:13824
	ds_read_b128 v[224:227], v78 offset:13888
	ds_read_b128 v[116:119], v78 offset:16128
	ds_read_b128 v[120:123], v78 offset:16192
	s_waitcnt vmcnt(1) lgkmcnt(15)
	v_mfma_f32_16x16x32_bf16 v[8:11], v[8:11], v[4:7], 0
	s_waitcnt vmcnt(0) lgkmcnt(14)
	v_mfma_f32_16x16x32_bf16 v[8:11], v[12:15], v[0:3], v[8:11]
	s_waitcnt lgkmcnt(0)
	v_mov_b32_e32 v12, 0
	v_mov_b32_e32 v13, 0
	v_mov_b32_e32 v14, 0
	v_mov_b32_e32 v15, 0
	s_and_saveexec_b64 s[0:1], s[10:11]
	s_cbranch_execz .LBB0_797
	v_mfma_f32_16x16x32_bf16 v[12:15], v[172:175], v[4:7], 0
	v_mfma_f32_16x16x32_bf16 v[12:15], v[176:179], v[0:3], v[12:15]
	v_mul_f32_e32 v16, v37, v45
	v_mul_f32_e32 v17, v37, v46
	v_mul_f32_e32 v18, v37, v47
	v_mul_f32_e32 v19, v37, v48
	v_exp_f32_e32 v16, v16
	v_exp_f32_e32 v17, v17
	v_exp_f32_e32 v18, v18
	v_exp_f32_e32 v19, v19
	v_pk_mul_f32 v[12:13], v[16:17], v[12:13]
	s_nop 0
	v_cndmask_b32_e64 v12, 0, v12, s[30:31]
	v_pk_mul_f32 v[14:15], v[18:19], v[14:15]
	v_cndmask_b32_e64 v13, 0, v13, s[28:29]
	v_cndmask_b32_e64 v14, 0, v14, s[26:27]
	v_cndmask_b32_e64 v15, 0, v15, s[24:25]
.LBB0_797:
	s_or_b64 exec, exec, s[0:1]
	v_mov_b32_e32 v24, 0
	v_mov_b32_e32 v82, 0
	v_mov_b32_e32 v83, 0
	v_mov_b32_e32 v85, 0
	v_mov_b32_e32 v87, 0
	s_and_saveexec_b64 s[0:1], s[12:13]
	s_cbranch_execz .LBB0_799
	v_mfma_f32_16x16x32_bf16 v[16:19], v[180:183], v[4:7], 0
	v_mfma_f32_16x16x32_bf16 v[16:19], v[184:187], v[0:3], v[16:19]
	v_mul_f32_e32 v20, v37, v49
	v_mul_f32_e32 v21, v37, v50
	v_mul_f32_e32 v22, v37, v51
	v_mul_f32_e32 v23, v37, v52
	v_exp_f32_e32 v20, v20
	v_exp_f32_e32 v21, v21
	v_exp_f32_e32 v22, v22
	v_exp_f32_e32 v23, v23
	v_pk_mul_f32 v[16:17], v[20:21], v[16:17]
	s_nop 0
	v_cndmask_b32_e64 v82, 0, v16, s[40:41]
	v_pk_mul_f32 v[18:19], v[22:23], v[18:19]
	v_cndmask_b32_e64 v83, 0, v17, s[38:39]
	v_cndmask_b32_e64 v85, 0, v18, s[36:37]
	v_cndmask_b32_e64 v87, 0, v19, s[34:35]
.LBB0_799:
	s_or_b64 exec, exec, s[0:1]
	v_mov_b32_e32 v95, 0
	v_mov_b32_e32 v96, 0
	v_mov_b32_e32 v98, 0
	s_and_saveexec_b64 s[0:1], s[14:15]
	s_cbranch_execz .LBB0_801
	v_mfma_f32_16x16x32_bf16 v[16:19], v[188:191], v[4:7], 0
	v_mfma_f32_16x16x32_bf16 v[16:19], v[192:195], v[0:3], v[16:19]
	v_mul_f32_e32 v20, v37, v53
	v_mul_f32_e32 v21, v37, v54
	v_mul_f32_e32 v22, v37, v55
	v_mul_f32_e32 v23, v37, v56
	v_exp_f32_e32 v20, v20
	v_exp_f32_e32 v21, v21
	v_exp_f32_e32 v22, v22
	v_exp_f32_e32 v23, v23
	v_pk_mul_f32 v[16:17], v[20:21], v[16:17]
	s_nop 0
	v_cndmask_b32_e64 v24, 0, v16, s[48:49]
	v_pk_mul_f32 v[18:19], v[22:23], v[18:19]
	v_cndmask_b32_e64 v95, 0, v17, s[46:47]
	v_cndmask_b32_e64 v96, 0, v18, s[44:45]
	v_cndmask_b32_e64 v98, 0, v19, s[42:43]
.LBB0_801:
	s_or_b64 exec, exec, s[0:1]
	v_mov_b32_e32 v81, 0
	v_mov_b32_e32 v84, 0
	v_mov_b32_e32 v86, 0
	v_mov_b32_e32 v88, 0
	v_mov_b32_e32 v89, 0
	s_and_saveexec_b64 s[0:1], s[16:17]
	s_cbranch_execz .LBB0_803
	v_mfma_f32_16x16x32_bf16 v[16:19], v[204:207], v[4:7], 0
	v_mfma_f32_16x16x32_bf16 v[16:19], v[208:211], v[0:3], v[16:19]
	v_mul_f32_e32 v20, v37, v57
	v_mul_f32_e32 v21, v37, v58
	v_mul_f32_e32 v22, v37, v59
	v_mul_f32_e32 v23, v37, v60
	v_exp_f32_e32 v20, v20
	v_exp_f32_e32 v21, v21
	v_exp_f32_e32 v22, v22
	v_exp_f32_e32 v23, v23
	v_pk_mul_f32 v[16:17], v[20:21], v[16:17]
	s_nop 0
	v_cndmask_b32_e64 v84, 0, v16, s[56:57]
	v_pk_mul_f32 v[18:19], v[22:23], v[18:19]
	v_cndmask_b32_e64 v86, 0, v17, s[54:55]
	v_cndmask_b32_e64 v88, 0, v18, s[52:53]
	v_cndmask_b32_e64 v89, 0, v19, s[50:51]
.LBB0_803:
	s_or_b64 exec, exec, s[0:1]
	v_mov_b32_e32 v97, 0
	v_mov_b32_e32 v99, 0
	v_mov_b32_e32 v100, 0
	s_and_saveexec_b64 s[0:1], s[18:19]
	s_cbranch_execz .LBB0_805
	v_mfma_f32_16x16x32_bf16 v[16:19], v[212:215], v[4:7], 0
	v_mfma_f32_16x16x32_bf16 v[16:19], v[216:219], v[0:3], v[16:19]
	v_mul_f32_e32 v20, v37, v61
	v_mul_f32_e32 v21, v37, v62
	v_mul_f32_e32 v22, v37, v63
	v_mul_f32_e32 v23, v37, v64
	v_exp_f32_e32 v20, v20
	v_exp_f32_e32 v21, v21
	v_exp_f32_e32 v22, v22
	v_exp_f32_e32 v23, v23
	v_pk_mul_f32 v[16:17], v[20:21], v[16:17]
	s_nop 0
	v_cndmask_b32_e64 v81, 0, v16, s[64:65]
	v_pk_mul_f32 v[18:19], v[22:23], v[18:19]
	v_cndmask_b32_e64 v97, 0, v17, s[62:63]
	v_cndmask_b32_e64 v99, 0, v18, s[60:61]
	v_cndmask_b32_e64 v100, 0, v19, s[58:59]
.LBB0_805:
	s_or_b64 exec, exec, s[0:1]
	v_mov_b32_e32 v90, 0
	v_mov_b32_e32 v91, 0
	v_mov_b32_e32 v92, 0
	v_mov_b32_e32 v93, 0
	v_mov_b32_e32 v94, 0
	s_and_saveexec_b64 s[0:1], s[82:83]
	s_cbranch_execz .LBB0_807
	v_mfma_f32_16x16x32_bf16 v[16:19], v[220:223], v[4:7], 0
	v_mfma_f32_16x16x32_bf16 v[16:19], v[224:227], v[0:3], v[16:19]
	v_mul_f32_e32 v20, v37, v65
	v_mul_f32_e32 v21, v37, v66
	v_mul_f32_e32 v22, v37, v67
	v_mul_f32_e32 v23, v37, v68
	v_exp_f32_e32 v20, v20
	v_exp_f32_e32 v21, v21
	v_exp_f32_e32 v22, v22
	v_exp_f32_e32 v23, v23
	v_pk_mul_f32 v[16:17], v[20:21], v[16:17]
	s_nop 0
	v_cndmask_b32_e64 v91, 0, v16, s[72:73]
	v_pk_mul_f32 v[18:19], v[22:23], v[18:19]
	v_cndmask_b32_e64 v92, 0, v17, s[70:71]
	v_cndmask_b32_e64 v93, 0, v18, s[68:69]
	v_cndmask_b32_e64 v94, 0, v19, s[66:67]
.LBB0_807:
	s_or_b64 exec, exec, s[0:1]
	v_mov_b32_e32 v101, 0
	v_mov_b32_e32 v102, 0
	v_mov_b32_e32 v103, 0
	s_and_saveexec_b64 s[0:1], s[84:85]
	s_cbranch_execz .LBB0_809
	v_mfma_f32_16x16x32_bf16 v[16:19], v[116:119], v[4:7], 0
	v_mfma_f32_16x16x32_bf16 v[16:19], v[120:123], v[0:3], v[16:19]
	v_mul_f32_e32 v20, v37, v69
	v_mul_f32_e32 v21, v37, v70
	v_mul_f32_e32 v22, v37, v71
	v_mul_f32_e32 v23, v37, v72
	v_exp_f32_e32 v20, v20
	v_exp_f32_e32 v21, v21
	v_exp_f32_e32 v22, v22
	v_exp_f32_e32 v23, v23
	v_pk_mul_f32 v[16:17], v[20:21], v[16:17]
	s_nop 0
	v_cndmask_b32_e64 v90, 0, v16, s[80:81]
	v_pk_mul_f32 v[18:19], v[22:23], v[18:19]
	v_cndmask_b32_e64 v101, 0, v17, s[78:79]
	v_cndmask_b32_e64 v102, 0, v18, s[76:77]
	v_cndmask_b32_e64 v103, 0, v19, s[74:75]
